# vp56 variant: P8 K-loop padded so all four pre-MFMA barriers sit at 4 mod 8 (all MFMA blocks 8-byte aligned)
# speedup vs baseline: 1.0048x; 1.0033x over previous
; __device__ __forceinline__ void xcd_barrier(const XcdBarrier& b) {
;     ...
;     }
;     __syncthreads();
.LBB0_814:
	s_or_b64 exec, exec, s[6:7]
	s_mov_b64 s[6:7], s[28:29]
	s_waitcnt lgkmcnt(0)
	v_mov_b32_e32 v0, v230
	v_mov_b32_e32 v8, v230
	s_barrier
	s_nop 0
	s_nop 0
	s_nop 0
	s_nop 0
	s_nop 0
	s_nop 0
	s_nop 0
	s_nop 0
	s_nop 0
	s_nop 0
	s_nop 0
	s_nop 0
	s_nop 0
	s_and_b64 vcc, exec, s[4:5]
	v_readfirstlane_b32 s1, v8
	s_cbranch_vccnz .LBB0_844
	s_ashr_i32 s3, s2, 31
	s_load_dwordx2 s[4:5], s[6:7], 0xe0
	s_lshr_b32 s6, s3, 29
	s_add_i32 s9, s2, s6
	s_and_b32 s6, s9, -8
	s_sub_i32 s10, s2, s6
	s_cmp_gt_i32 s10, -1
	s_cbranch_scc0 .LBB0_817
	s_lshl_b32 s8, s10, 7
	s_cbranch_execz .LBB0_818
	s_branch .LBB0_819
